# PE: SwiGLU activation tiles stored write-through so they do not displace the re-read GEMM operands from L2
# baseline (speedup 1.0000x reference)
; __device__ __forceinline__ unsigned cvt_pk_bf16(float lo, float hi) { f32x2c v = {lo, hi}; bf16x2c b = __builtin_convertvector(v, bf16x2c); return __builtin_bit_cast(unsigned, b); }
;     __device__ __forceinline__ void operator()(f32x4 (&acc)[2][2][4][2], const Unit& u, int wr, int wc, int fr, int fq) const {
;     ...
;         for (int ai = 0; ai < 2; ++ai)
; #pragma unroll
;             for (int m = 0; m < 4; ++m) {
;                 const int row = row0 + ai * HALF + m * 16;
;                 const float rs = rtab[wr * 64 + fr + ai * HALF + m * 16], nl = -1.4426950408889634f * rs, rs2 = rs * rs;
;                 f32x4 o[2];
; #pragma unroll
;                 for (int n = 0; n < 2; ++n) {
;                     const f32x4 ag = acc[ai][0][m][n], gu = acc[ai][0][m][n] * acc[ai][1][m][n] * rs2;
; #pragma unroll
;                     for (int e = 0; e < 4; ++e) o[n][e] = gu[e] * __builtin_amdgcn_rcpf(1.0f + __builtin_amdgcn_exp2f(ag[e] * nl));
;                 }
;                 u32x4 w; w.x = cvt_pk_bf16(o[0][0], o[0][1]); w.y = cvt_pk_bf16(o[0][2], o[0][3]); w.z = cvt_pk_bf16(o[1][0], o[1][1]); w.w = cvt_pk_bf16(o[1][2], o[1][3]);
;                 *(u32x4*)(O + (size_t)row * 3328 + col0) = w;
;             }
.LBB0_785:
	ds_read2_b32 v[150:151], v145 offset1:16
	v_pk_mul_f32 v[124:125], v[128:129], v[124:125]
	v_pk_mul_f32 v[126:127], v[130:131], v[126:127]
	v_pk_mul_f32 v[118:119], v[122:123], v[118:119]
	v_pk_mul_f32 v[116:117], v[120:121], v[116:117]
	s_waitcnt lgkmcnt(0)
	v_mul_f32_e32 v149, 0xbfb8aa3b, v150
	v_mul_f32_e32 v153, v128, v149
	v_mul_f32_e32 v154, v129, v149
	v_mul_f32_e32 v128, v130, v149
	v_mul_f32_e32 v129, v131, v149
	v_exp_f32_e32 v128, v128
	v_exp_f32_e32 v129, v129
	v_mul_f32_e32 v130, v120, v149
	v_mul_f32_e32 v131, v121, v149
	v_add_f32_e32 v128, 1.0, v128
	v_add_f32_e32 v129, 1.0, v129
	v_rcp_f32_e32 v128, v128
	v_rcp_f32_e32 v129, v129
	v_exp_f32_e32 v130, v130
	v_exp_f32_e32 v131, v131
	v_mul_f32_e32 v122, v122, v149
	v_mul_f32_e32 v123, v123, v149
	v_exp_f32_e32 v155, v153
	v_exp_f32_e32 v154, v154
	v_exp_f32_e32 v122, v122
	v_exp_f32_e32 v123, v123
	v_mul_f32_e32 v150, v150, v150
	v_pk_mul_f32 v[126:127], v[126:127], v[150:151] op_sel_hi:[1,0]
	v_add_f32_e32 v155, 1.0, v155
	v_pk_mul_f32 v[126:127], v[126:127], v[128:129]
	v_add_f32_e32 v128, 1.0, v130
	v_add_f32_e32 v129, 1.0, v131
	v_add_f32_e32 v156, 1.0, v154
	v_rcp_f32_e32 v128, v128
	v_rcp_f32_e32 v129, v129
	v_add_f32_e32 v120, 1.0, v122
	v_add_f32_e32 v121, 1.0, v123
	v_rcp_f32_e32 v154, v155
	v_rcp_f32_e32 v155, v156
	v_rcp_f32_e32 v120, v120
	v_rcp_f32_e32 v121, v121
	v_pk_mul_f32 v[116:117], v[116:117], v[150:151] op_sel_hi:[1,0]
	v_lshl_or_b32 v152, s37, 7, v146
	v_pk_mul_f32 v[124:125], v[124:125], v[150:151] op_sel_hi:[1,0]
	v_pk_mul_f32 v[116:117], v[116:117], v[128:129]
	v_pk_mul_f32 v[118:119], v[118:119], v[150:151] op_sel_hi:[1,0]
	v_lshl_add_u32 v148, s72, 8, v67
	v_ashrrev_i32_e32 v153, 31, v152
	v_pk_mul_f32 v[124:125], v[124:125], v[154:155]
	v_pk_mul_f32 v[118:119], v[118:119], v[120:121]
	v_cvt_pk_bf16_f32 v122, v116, v117
	v_mov_b64_e32 v[116:117], s[94:95]
	v_cvt_pk_bf16_f32 v120, v124, v125
	v_cvt_pk_bf16_f32 v123, v118, v119
	v_mad_i64_i32 v[124:125], s[30:31], v148, s82, v[116:117]
	v_lshlrev_b64 v[118:119], 1, v[152:153]
	v_cvt_pk_bf16_f32 v121, v126, v127
	v_lshl_add_u64 v[124:125], v[124:125], 0, v[118:119]
	global_store_dwordx4 v[124:125], v[120:123], off sc1
	v_pk_mul_f32 v[108:109], v[112:113], v[108:109]
	v_pk_mul_f32 v[110:111], v[114:115], v[110:111]
	v_mul_f32_e32 v121, 0xbfb8aa3b, v151
	v_mul_f32_e32 v120, v112, v121
	v_exp_f32_e32 v122, v120
	v_mul_f32_e32 v120, v113, v121
	v_mul_f32_e32 v112, v114, v121
	v_mul_f32_e32 v113, v115, v121
	v_exp_f32_e32 v112, v112
	v_exp_f32_e32 v113, v113
	v_mul_f32_e32 v114, v104, v121
	v_mul_f32_e32 v115, v105, v121
	v_add_f32_e32 v112, 1.0, v112
	v_add_f32_e32 v113, 1.0, v113
	v_rcp_f32_e32 v112, v112
	v_rcp_f32_e32 v113, v113
	v_exp_f32_e32 v114, v114
	v_exp_f32_e32 v115, v115
	v_pk_mul_f32 v[102:103], v[106:107], v[102:103]
	v_mul_f32_e32 v106, v106, v121
	v_mul_f32_e32 v107, v107, v121
	v_exp_f32_e32 v106, v106
	v_exp_f32_e32 v107, v107
	v_exp_f32_e32 v123, v120
	v_mul_f32_e32 v120, v151, v151
	v_pk_mul_f32 v[110:111], v[110:111], v[120:121] op_sel_hi:[1,0]
	v_pk_mul_f32 v[100:101], v[104:105], v[100:101]
	v_pk_mul_f32 v[110:111], v[110:111], v[112:113]
	v_add_f32_e32 v112, 1.0, v114
	v_add_f32_e32 v113, 1.0, v115
	v_rcp_f32_e32 v112, v112
	v_rcp_f32_e32 v113, v113
	v_add_f32_e32 v104, 1.0, v106
	v_add_f32_e32 v105, 1.0, v107
	v_rcp_f32_e32 v104, v104
	v_rcp_f32_e32 v105, v105
	v_pk_mul_f32 v[100:101], v[100:101], v[120:121] op_sel_hi:[1,0]
	v_add_f32_e32 v122, 1.0, v122
	v_add_f32_e32 v123, 1.0, v123
	v_pk_mul_f32 v[106:107], v[100:101], v[112:113]
	v_pk_mul_f32 v[100:101], v[102:103], v[120:121] op_sel_hi:[1,0]
	v_rcp_f32_e32 v122, v122
	v_rcp_f32_e32 v123, v123
	v_pk_mul_f32 v[104:105], v[100:101], v[104:105]
	v_pk_mul_f32 v[108:109], v[108:109], v[120:121] op_sel_hi:[1,0]
	v_cvt_pk_bf16_f32 v103, v104, v105
	ds_read2_b32 v[104:105], v145 offset0:32 offset1:48
	v_or_b32_e32 v112, 16, v148
	v_pk_mul_f32 v[108:109], v[108:109], v[122:123]
	v_cvt_pk_bf16_f32 v102, v106, v107
	v_mad_i64_i32 v[106:107], s[30:31], v112, s82, v[116:117]
	v_cvt_pk_bf16_f32 v100, v108, v109
	v_cvt_pk_bf16_f32 v101, v110, v111
	v_lshl_add_u64 v[106:107], v[106:107], 0, v[118:119]
	global_store_dwordx4 v[106:107], v[100:103], off sc1
	v_pk_mul_f32 v[92:93], v[96:97], v[92:93]
	v_pk_mul_f32 v[94:95], v[98:99], v[94:95]
	s_waitcnt lgkmcnt(0)
; __device__ __forceinline__ unsigned cvt_pk_bf16(float lo, float hi) { f32x2c v = {lo, hi}; bf16x2c b = __builtin_convertvector(v, bf16x2c); return __builtin_bit_cast(unsigned, b); }
;     __device__ __forceinline__ void operator()(f32x4 (&acc)[2][2][4][2], const Unit& u, int wr, int wc, int fr, int fq) const {
;     ...
;         for (int ai = 0; ai < 2; ++ai)
; #pragma unroll
;             for (int m = 0; m < 4; ++m) {
;                 const int row = row0 + ai * HALF + m * 16;
;                 const float rs = rtab[wr * 64 + fr + ai * HALF + m * 16], nl = -1.4426950408889634f * rs, rs2 = rs * rs;
;                 f32x4 o[2];
; #pragma unroll
;                 for (int n = 0; n < 2; ++n) {
;                     const f32x4 ag = acc[ai][0][m][n], gu = acc[ai][0][m][n] * acc[ai][1][m][n] * rs2;
; #pragma unroll
;                     for (int e = 0; e < 4; ++e) o[n][e] = gu[e] * __builtin_amdgcn_rcpf(1.0f + __builtin_amdgcn_exp2f(ag[e] * nl));
;                 }
;                 u32x4 w; w.x = cvt_pk_bf16(o[0][0], o[0][1]); w.y = cvt_pk_bf16(o[0][2], o[0][3]); w.z = cvt_pk_bf16(o[1][0], o[1][1]); w.w = cvt_pk_bf16(o[1][2], o[1][3]);
;                 *(u32x4*)(O + (size_t)row * 3328 + col0) = w;
;             }
	v_mul_f32_e32 v101, 0xbfb8aa3b, v104
	v_mul_f32_e32 v100, v96, v101
	v_exp_f32_e32 v102, v100
	v_mul_f32_e32 v100, v97, v101
	v_mul_f32_e32 v96, v98, v101
	v_mul_f32_e32 v97, v99, v101
	v_exp_f32_e32 v96, v96
	v_exp_f32_e32 v97, v97
	v_mul_f32_e32 v98, v88, v101
	v_mul_f32_e32 v99, v89, v101
	v_add_f32_e32 v96, 1.0, v96
	v_add_f32_e32 v97, 1.0, v97
	v_rcp_f32_e32 v96, v96
	v_rcp_f32_e32 v97, v97
	v_exp_f32_e32 v98, v98
	v_exp_f32_e32 v99, v99
	v_pk_mul_f32 v[86:87], v[90:91], v[86:87]
	v_mul_f32_e32 v90, v90, v101
	v_mul_f32_e32 v91, v91, v101
	v_exp_f32_e32 v90, v90
	v_exp_f32_e32 v91, v91
	v_exp_f32_e32 v103, v100
	v_mul_f32_e32 v100, v104, v104
	v_pk_mul_f32 v[94:95], v[94:95], v[100:101] op_sel_hi:[1,0]
	v_pk_mul_f32 v[84:85], v[88:89], v[84:85]
	v_pk_mul_f32 v[94:95], v[94:95], v[96:97]
	v_add_f32_e32 v96, 1.0, v98
	v_add_f32_e32 v97, 1.0, v99
	v_rcp_f32_e32 v96, v96
	v_rcp_f32_e32 v97, v97
	v_add_f32_e32 v88, 1.0, v90
	v_add_f32_e32 v89, 1.0, v91
	v_add_f32_e32 v102, 1.0, v102
	v_add_f32_e32 v103, 1.0, v103
	v_rcp_f32_e32 v88, v88
	v_rcp_f32_e32 v89, v89
	v_rcp_f32_e32 v102, v102
	v_rcp_f32_e32 v103, v103
	v_pk_mul_f32 v[84:85], v[84:85], v[100:101] op_sel_hi:[1,0]
	v_pk_mul_f32 v[92:93], v[92:93], v[100:101] op_sel_hi:[1,0]
	v_pk_mul_f32 v[90:91], v[84:85], v[96:97]
	v_pk_mul_f32 v[84:85], v[86:87], v[100:101] op_sel_hi:[1,0]
	v_or_b32_e32 v96, 32, v148
	v_pk_mul_f32 v[88:89], v[84:85], v[88:89]
	v_pk_mul_f32 v[92:93], v[92:93], v[102:103]
	v_cvt_pk_bf16_f32 v87, v88, v89
	v_mad_i64_i32 v[88:89], s[30:31], v96, s82, v[116:117]
	v_cvt_pk_bf16_f32 v84, v92, v93
	v_cvt_pk_bf16_f32 v85, v94, v95
	v_cvt_pk_bf16_f32 v86, v90, v91
	v_lshl_add_u64 v[88:89], v[88:89], 0, v[118:119]
	global_store_dwordx4 v[88:89], v[84:87], off sc1
	v_pk_mul_f32 v[76:77], v[80:81], v[76:77]
	v_pk_mul_f32 v[78:79], v[82:83], v[78:79]
	v_mul_f32_e32 v85, 0xbfb8aa3b, v105
	v_mul_f32_e32 v84, v80, v85
	v_exp_f32_e32 v86, v84
	v_mul_f32_e32 v84, v81, v85
	v_mul_f32_e32 v80, v82, v85
	v_mul_f32_e32 v81, v83, v85
	v_exp_f32_e32 v80, v80
	v_exp_f32_e32 v81, v81
	v_mul_f32_e32 v82, v72, v85
	v_mul_f32_e32 v83, v73, v85
	v_add_f32_e32 v80, 1.0, v80
	v_add_f32_e32 v81, 1.0, v81
	v_rcp_f32_e32 v80, v80
	v_rcp_f32_e32 v81, v81
	v_exp_f32_e32 v82, v82
	v_exp_f32_e32 v83, v83
	v_pk_mul_f32 v[70:71], v[74:75], v[70:71]
	v_mul_f32_e32 v74, v74, v85
	v_mul_f32_e32 v75, v75, v85
	v_exp_f32_e32 v74, v74
	v_exp_f32_e32 v75, v75
	v_exp_f32_e32 v87, v84
	v_mul_f32_e32 v84, v105, v105
	v_pk_mul_f32 v[78:79], v[78:79], v[84:85] op_sel_hi:[1,0]
	v_pk_mul_f32 v[68:69], v[72:73], v[68:69]
	v_pk_mul_f32 v[78:79], v[78:79], v[80:81]
	v_add_f32_e32 v80, 1.0, v82
	v_add_f32_e32 v81, 1.0, v83
	v_rcp_f32_e32 v80, v80
	v_rcp_f32_e32 v81, v81
	v_add_f32_e32 v72, 1.0, v74
	v_add_f32_e32 v73, 1.0, v75
	v_rcp_f32_e32 v72, v72
	v_rcp_f32_e32 v73, v73
	v_pk_mul_f32 v[68:69], v[68:69], v[84:85] op_sel_hi:[1,0]
	v_add_f32_e32 v86, 1.0, v86
	v_add_f32_e32 v87, 1.0, v87
	v_pk_mul_f32 v[74:75], v[68:69], v[80:81]
	v_pk_mul_f32 v[68:69], v[70:71], v[84:85] op_sel_hi:[1,0]
	v_rcp_f32_e32 v86, v86
	v_rcp_f32_e32 v87, v87
	v_pk_mul_f32 v[72:73], v[68:69], v[72:73]
	v_pk_mul_f32 v[76:77], v[76:77], v[84:85] op_sel_hi:[1,0]
	v_cvt_pk_bf16_f32 v71, v72, v73
	ds_read2_b32 v[72:73], v145 offset0:128 offset1:144
	v_or_b32_e32 v80, 48, v148
	v_pk_mul_f32 v[76:77], v[76:77], v[86:87]
	v_cvt_pk_bf16_f32 v70, v74, v75
	v_mad_i64_i32 v[74:75], s[30:31], v80, s82, v[116:117]
	v_cvt_pk_bf16_f32 v68, v76, v77
	v_cvt_pk_bf16_f32 v69, v78, v79
	v_lshl_add_u64 v[74:75], v[74:75], 0, v[118:119]
	global_store_dwordx4 v[74:75], v[68:71], off sc1
	s_waitcnt lgkmcnt(0)
	v_mul_f32_e32 v74, 0xbfb8aa3b, v72
	v_pk_mul_f32 v[58:59], v[62:63], v[58:59]
	v_mul_f32_e32 v68, v62, v74
	v_exp_f32_e32 v70, v68
	v_mul_f32_e32 v68, v63, v74
	v_mul_f32_e32 v62, v64, v74
	v_mul_f32_e32 v63, v65, v74
	v_exp_f32_e32 v62, v62
	v_exp_f32_e32 v63, v63
	v_pk_mul_f32 v[60:61], v[64:65], v[60:61]
	v_mul_f32_e32 v64, v54, v74
	v_add_f32_e32 v62, 1.0, v62
	v_add_f32_e32 v63, 1.0, v63
	v_mul_f32_e32 v65, v55, v74
	v_rcp_f32_e32 v62, v62
	v_rcp_f32_e32 v63, v63
	v_exp_f32_e32 v64, v64
	v_exp_f32_e32 v65, v65
	v_pk_mul_f32 v[52:53], v[56:57], v[52:53]
	v_mul_f32_e32 v56, v56, v74
	v_mul_f32_e32 v57, v57, v74
	v_exp_f32_e32 v56, v56
	v_exp_f32_e32 v57, v57
	v_add_u32_e32 v69, 0x80, v148
	v_exp_f32_e32 v71, v68
	v_mul_f32_e32 v68, v72, v72
	v_pk_mul_f32 v[60:61], v[60:61], v[68:69] op_sel_hi:[1,0]
	v_pk_mul_f32 v[50:51], v[54:55], v[50:51]
	v_pk_mul_f32 v[60:61], v[60:61], v[62:63]
	v_add_f32_e32 v62, 1.0, v64
	v_add_f32_e32 v63, 1.0, v65
	v_rcp_f32_e32 v62, v62
	v_rcp_f32_e32 v63, v63
	v_add_f32_e32 v54, 1.0, v56
	v_add_f32_e32 v55, 1.0, v57
	v_add_f32_e32 v70, 1.0, v70
	v_add_f32_e32 v71, 1.0, v71
	v_rcp_f32_e32 v54, v54
	v_rcp_f32_e32 v55, v55
	v_rcp_f32_e32 v70, v70
	v_rcp_f32_e32 v71, v71
	v_pk_mul_f32 v[50:51], v[50:51], v[68:69] op_sel_hi:[1,0]
	v_pk_mul_f32 v[58:59], v[58:59], v[68:69] op_sel_hi:[1,0]
	v_pk_mul_f32 v[56:57], v[50:51], v[62:63]
	v_pk_mul_f32 v[50:51], v[52:53], v[68:69] op_sel_hi:[1,0]
	v_pk_mul_f32 v[58:59], v[58:59], v[70:71]
	v_pk_mul_f32 v[54:55], v[50:51], v[54:55]
	v_cvt_pk_bf16_f32 v50, v58, v59
	v_cvt_pk_bf16_f32 v53, v54, v55
	v_mad_i64_i32 v[54:55], s[30:31], v69, s82, v[116:117]
	v_cvt_pk_bf16_f32 v51, v60, v61
	v_cvt_pk_bf16_f32 v52, v56, v57
	v_lshl_add_u64 v[54:55], v[54:55], 0, v[118:119]
	global_store_dwordx4 v[54:55], v[50:53], off sc1
	v_pk_mul_f32 v[42:43], v[46:47], v[42:43]
	v_pk_mul_f32 v[44:45], v[48:49], v[44:45]
; __device__ __forceinline__ unsigned cvt_pk_bf16(float lo, float hi) { f32x2c v = {lo, hi}; bf16x2c b = __builtin_convertvector(v, bf16x2c); return __builtin_bit_cast(unsigned, b); }
; #define PG8_BAR __builtin_amdgcn_s_barrier()
;     __device__ __forceinline__ void operator()(f32x4 (&acc)[2][2][4][2], const Unit& u, int wr, int wc, int fr, int fq) const {
;     ...
;         for (int ai = 0; ai < 2; ++ai)
; #pragma unroll
;             for (int m = 0; m < 4; ++m) {
;                 const int row = row0 + ai * HALF + m * 16;
;                 const float rs = rtab[wr * 64 + fr + ai * HALF + m * 16], nl = -1.4426950408889634f * rs, rs2 = rs * rs;
;                 f32x4 o[2];
; #pragma unroll
;                 for (int n = 0; n < 2; ++n) {
;                     const f32x4 ag = acc[ai][0][m][n], gu = acc[ai][0][m][n] * acc[ai][1][m][n] * rs2;
; #pragma unroll
;                     for (int e = 0; e < 4; ++e) o[n][e] = gu[e] * __builtin_amdgcn_rcpf(1.0f + __builtin_amdgcn_exp2f(ag[e] * nl));
;                 }
;                 u32x4 w; w.x = cvt_pk_bf16(o[0][0], o[0][1]); w.y = cvt_pk_bf16(o[0][2], o[0][3]); w.z = cvt_pk_bf16(o[1][0], o[1][1]); w.w = cvt_pk_bf16(o[1][2], o[1][3]);
;                 *(u32x4*)(O + (size_t)row * 3328 + col0) = w;
;             }
; template <class Epi, class Sched, bool ALIGN_EPI = false, bool SP2 = false>
; __device__ __forceinline__ void gemm_phase(PG8_LAS unsigned char* lds, const Gemm g, const Sched& S, const Epi& E) {
;     ...
;         cur = nxt; cA = nA; cB = nB; ++ui;
;         if constexpr (ALIGN_EPI) { if (wr == 1) PG8_BAR; }
	v_mul_f32_e32 v51, 0xbfb8aa3b, v73
	v_mul_f32_e32 v50, v46, v51
	v_exp_f32_e32 v52, v50
	v_mul_f32_e32 v50, v47, v51
	v_mul_f32_e32 v46, v48, v51
	v_mul_f32_e32 v47, v49, v51
	v_exp_f32_e32 v46, v46
	v_exp_f32_e32 v47, v47
	v_mul_f32_e32 v48, v38, v51
	v_mul_f32_e32 v49, v39, v51
	v_add_f32_e32 v46, 1.0, v46
	v_add_f32_e32 v47, 1.0, v47
	v_rcp_f32_e32 v46, v46
	v_rcp_f32_e32 v47, v47
	v_exp_f32_e32 v48, v48
	v_exp_f32_e32 v49, v49
	v_pk_mul_f32 v[36:37], v[40:41], v[36:37]
	v_mul_f32_e32 v40, v40, v51
	v_mul_f32_e32 v41, v41, v51
	v_exp_f32_e32 v40, v40
	v_exp_f32_e32 v41, v41
	v_exp_f32_e32 v53, v50
	v_mul_f32_e32 v50, v73, v73
	v_pk_mul_f32 v[44:45], v[44:45], v[50:51] op_sel_hi:[1,0]
	v_pk_mul_f32 v[34:35], v[38:39], v[34:35]
	v_pk_mul_f32 v[44:45], v[44:45], v[46:47]
	v_add_f32_e32 v46, 1.0, v48
	v_add_f32_e32 v47, 1.0, v49
	v_rcp_f32_e32 v46, v46
	v_rcp_f32_e32 v47, v47
	v_add_f32_e32 v38, 1.0, v40
	v_add_f32_e32 v39, 1.0, v41
	v_rcp_f32_e32 v38, v38
	v_rcp_f32_e32 v39, v39
	v_pk_mul_f32 v[34:35], v[34:35], v[50:51] op_sel_hi:[1,0]
	v_add_f32_e32 v52, 1.0, v52
	v_add_f32_e32 v53, 1.0, v53
	v_pk_mul_f32 v[40:41], v[34:35], v[46:47]
	v_pk_mul_f32 v[34:35], v[36:37], v[50:51] op_sel_hi:[1,0]
	v_rcp_f32_e32 v52, v52
	v_rcp_f32_e32 v53, v53
	v_pk_mul_f32 v[38:39], v[34:35], v[38:39]
	v_pk_mul_f32 v[42:43], v[42:43], v[50:51] op_sel_hi:[1,0]
	v_cvt_pk_bf16_f32 v37, v38, v39
	ds_read2_b32 v[38:39], v145 offset0:160 offset1:176
	v_add_u32_e32 v46, 0x90, v148
	v_pk_mul_f32 v[42:43], v[42:43], v[52:53]
	v_cvt_pk_bf16_f32 v36, v40, v41
	v_mad_i64_i32 v[40:41], s[30:31], v46, s82, v[116:117]
	v_cvt_pk_bf16_f32 v34, v42, v43
	v_cvt_pk_bf16_f32 v35, v44, v45
	v_lshl_add_u64 v[40:41], v[40:41], 0, v[118:119]
	global_store_dwordx4 v[40:41], v[34:37], off sc1
	v_pk_mul_f32 v[26:27], v[30:31], v[26:27]
	v_pk_mul_f32 v[28:29], v[32:33], v[28:29]
	s_waitcnt lgkmcnt(0)
	v_mul_f32_e32 v35, 0xbfb8aa3b, v38
	v_mul_f32_e32 v34, v30, v35
	v_exp_f32_e32 v36, v34
	v_mul_f32_e32 v34, v31, v35
	v_mul_f32_e32 v30, v32, v35
	v_mul_f32_e32 v31, v33, v35
	v_exp_f32_e32 v30, v30
	v_exp_f32_e32 v31, v31
	v_mul_f32_e32 v32, v22, v35
	v_mul_f32_e32 v33, v23, v35
	v_add_f32_e32 v30, 1.0, v30
	v_add_f32_e32 v31, 1.0, v31
	v_rcp_f32_e32 v30, v30
	v_rcp_f32_e32 v31, v31
	v_exp_f32_e32 v32, v32
	v_exp_f32_e32 v33, v33
	v_pk_mul_f32 v[20:21], v[24:25], v[20:21]
	v_mul_f32_e32 v24, v24, v35
	v_mul_f32_e32 v25, v25, v35
	v_exp_f32_e32 v24, v24
	v_exp_f32_e32 v25, v25
	v_exp_f32_e32 v37, v34
	v_mul_f32_e32 v34, v38, v38
	v_pk_mul_f32 v[28:29], v[28:29], v[34:35] op_sel_hi:[1,0]
	v_pk_mul_f32 v[18:19], v[22:23], v[18:19]
	v_pk_mul_f32 v[28:29], v[28:29], v[30:31]
	v_add_f32_e32 v30, 1.0, v32
	v_add_f32_e32 v31, 1.0, v33
	v_rcp_f32_e32 v30, v30
	v_rcp_f32_e32 v31, v31
	v_add_f32_e32 v22, 1.0, v24
	v_add_f32_e32 v23, 1.0, v25
	v_add_f32_e32 v36, 1.0, v36
	v_add_f32_e32 v37, 1.0, v37
	v_rcp_f32_e32 v22, v22
	v_rcp_f32_e32 v23, v23
	v_rcp_f32_e32 v36, v36
	v_rcp_f32_e32 v37, v37
	v_pk_mul_f32 v[18:19], v[18:19], v[34:35] op_sel_hi:[1,0]
	v_pk_mul_f32 v[26:27], v[26:27], v[34:35] op_sel_hi:[1,0]
	v_pk_mul_f32 v[24:25], v[18:19], v[30:31]
	v_pk_mul_f32 v[18:19], v[20:21], v[34:35] op_sel_hi:[1,0]
	v_add_u32_e32 v30, 0xa0, v148
	v_pk_mul_f32 v[22:23], v[18:19], v[22:23]
	v_pk_mul_f32 v[26:27], v[26:27], v[36:37]
	v_cvt_pk_bf16_f32 v21, v22, v23
	v_mad_i64_i32 v[22:23], s[30:31], v30, s82, v[116:117]
	v_cvt_pk_bf16_f32 v18, v26, v27
	v_cvt_pk_bf16_f32 v19, v28, v29
	v_cvt_pk_bf16_f32 v20, v24, v25
	v_lshl_add_u64 v[22:23], v[22:23], 0, v[118:119]
	global_store_dwordx4 v[22:23], v[18:21], off sc1
	v_pk_mul_f32 v[10:11], v[14:15], v[10:11]
	v_pk_mul_f32 v[12:13], v[16:17], v[12:13]
	v_mul_f32_e32 v19, 0xbfb8aa3b, v39
	v_mul_f32_e32 v18, v14, v19
	v_exp_f32_e32 v20, v18
	v_mul_f32_e32 v18, v15, v19
	v_mul_f32_e32 v14, v16, v19
	v_mul_f32_e32 v15, v17, v19
	v_exp_f32_e32 v14, v14
	v_exp_f32_e32 v15, v15
	v_mul_f32_e32 v16, v6, v19
	v_mul_f32_e32 v17, v7, v19
	v_add_f32_e32 v14, 1.0, v14
	v_add_f32_e32 v15, 1.0, v15
	v_rcp_f32_e32 v14, v14
	v_rcp_f32_e32 v15, v15
	v_exp_f32_e32 v16, v16
	v_exp_f32_e32 v17, v17
	v_pk_mul_f32 v[4:5], v[8:9], v[4:5]
	v_mul_f32_e32 v8, v8, v19
	v_mul_f32_e32 v9, v9, v19
	v_exp_f32_e32 v8, v8
	v_exp_f32_e32 v9, v9
	v_exp_f32_e32 v21, v18
	v_mul_f32_e32 v18, v39, v39
	v_pk_mul_f32 v[12:13], v[12:13], v[18:19] op_sel_hi:[1,0]
	v_pk_mul_f32 v[2:3], v[6:7], v[2:3]
	v_pk_mul_f32 v[12:13], v[12:13], v[14:15]
	v_add_f32_e32 v14, 1.0, v16
	v_add_f32_e32 v15, 1.0, v17
	v_rcp_f32_e32 v14, v14
	v_rcp_f32_e32 v15, v15
	v_add_f32_e32 v6, 1.0, v8
	v_add_f32_e32 v7, 1.0, v9
	v_add_f32_e32 v20, 1.0, v20
	v_add_f32_e32 v21, 1.0, v21
	v_rcp_f32_e32 v6, v6
	v_rcp_f32_e32 v7, v7
	v_rcp_f32_e32 v20, v20
	v_rcp_f32_e32 v21, v21
	v_pk_mul_f32 v[2:3], v[2:3], v[18:19] op_sel_hi:[1,0]
	v_pk_mul_f32 v[10:11], v[10:11], v[18:19] op_sel_hi:[1,0]
	v_pk_mul_f32 v[8:9], v[2:3], v[14:15]
	v_pk_mul_f32 v[2:3], v[4:5], v[18:19] op_sel_hi:[1,0]
	v_add_u32_e32 v14, 0xb0, v148
	v_pk_mul_f32 v[6:7], v[2:3], v[6:7]
	v_pk_mul_f32 v[10:11], v[10:11], v[20:21]
	v_cvt_pk_bf16_f32 v5, v6, v7
	v_mad_i64_i32 v[6:7], s[30:31], v14, s82, v[116:117]
	v_cvt_pk_bf16_f32 v2, v10, v11
	v_cvt_pk_bf16_f32 v3, v12, v13
	v_cvt_pk_bf16_f32 v4, v8, v9
	v_lshl_add_u64 v[6:7], v[6:7], 0, v[118:119]
	s_andn2_b64 vcc, exec, s[50:51]
	s_mov_b64 s[50:51], -1
	global_store_dwordx4 v[6:7], v[2:5], off sc1
	s_cbranch_vccnz .LBB0_778
	s_andn2_b64 vcc, exec, s[42:43]
	s_cbranch_vccnz .LBB0_777
	s_barrier
	s_branch .LBB0_777
